# v102 chain order + trailing-half LDS read hoist in the up K-loop (re-test of the v86 idea on the new MFMA order)
# baseline (speedup 1.0000x reference)
; #define PG8_STAGE(bufoff, gbase, voff) do { _Pragma("unroll") for (int _i = 0; _i < 2; ++_i) \
;         __builtin_amdgcn_global_load_lds((const unsigned*)((const char*)(gbase) + (voff)[_i]), (PG8_LAS unsigned*)(lds + (bufoff) + ldsw + _i * 8192), 16, 0, 0); } while (0)
; #define PG8_LDA(dst, b, h) do { _Pragma("unroll") for (int m = 0; m < 4; ++m) _Pragma("unroll") for (int k = 0; k < 2; ++k) dst[m][k] = *(const PG8_LAS bf16x8*)(lds + PG8_SA(b, h) + aoff + m * 2048 + k * 1024); } while (0)
; #define PG8_LDB(dst, b, h) do { _Pragma("unroll") for (int n = 0; n < 2; ++n) _Pragma("unroll") for (int k = 0; k < 2; ++k) dst[n][k] = *(const PG8_LAS bf16x8*)(lds + PG8_SB(b, h) + boff + n * 2048 + k * 1024); } while (0)
; #define PG8_MMA(ai, bj, At, Bt) do { __builtin_amdgcn_s_setprio(1); _Pragma("unroll") for (int m = 0; m < 4; ++m) _Pragma("unroll") for (int n = 0; n < 2; ++n) _Pragma("unroll") for (int k = 0; k < 2; ++k) \
;         acc[ai][bj][m][n] = __builtin_amdgcn_mfma_f32_16x16x32_bf16(Bt[n][k], At[m][k], acc[ai][bj][m][n], 0, 0, 0); __builtin_amdgcn_s_setprio(0); } while (0)
; #define PG8_WAIT_V(n) asm volatile("s_waitcnt vmcnt(" #n ")" ::: "memory")
; #define PG8_WAIT_L(n) asm volatile("s_waitcnt lgkmcnt(" #n ")" ::: "memory")
; #define PG8_BAR __builtin_amdgcn_s_barrier()
; #define PG8_SCHED __builtin_amdgcn_sched_barrier(0)
; template <class Epi, class Sched, bool ALIGN_EPI = false, bool SP2 = false>
; __device__ __forceinline__ void gemm_phase(PG8_LAS unsigned char* lds, const Gemm g, const Sched& S, const Epi& E) {
;     ...
;             PG8_LDB(B0, 0, 0); PG8_LDB(B1, 0, 1); PG8_SCHED; PG8_LDA(At, 0, 0); PG8_STAGE(PG8_SA(1, 1), a1 + hstep, voffA);
;             PG8_WAIT_V(8); PG8_WAIT_L(0); PG8_BAR; PG8_MMA(0, 0, At, B0); PG8_MMA(0, 1, At, B1); PG8_BAR; PG8_SCHED;
;             PG8_LDA(At, 0, 1); PG8_STAGE(PG8_SB(0, 0), b2, voffB); PG8_STAGE(PG8_SB(0, 1), b2 + hstep, voffB); PG8_STAGE(PG8_SA(0, 0), a2, voffA);
;             PG8_WAIT_V(8); PG8_WAIT_L(0); PG8_BAR; PG8_MMA(1, 0, At, B0); PG8_MMA(1, 1, At, B1); PG8_BAR; PG8_SCHED;
;             PG8_LDB(B0, 1, 0); PG8_LDB(B1, 1, 1); PG8_SCHED; PG8_LDA(At, 1, 0); PG8_STAGE(PG8_SA(0, 1), a2 + hstep, voffA);
.Lup_peel_w1:
	ds_read_b128 v[140:143], v254
	ds_read_b128 v[168:171], v254 offset:1024
	ds_read_b128 v[172:175], v254 offset:2048
	ds_read_b128 v[176:179], v254 offset:3072
	ds_read_b128 v[180:183], v254 offset:16384
	ds_read_b128 v[184:187], v254 offset:17408
	ds_read_b128 v[188:191], v254 offset:18432
	ds_read_b128 v[210:213], v254 offset:19456
	s_add_u32 s16, s14, 0xfffc0080
	s_addc_u32 s17, s15, -1
	s_cmp_eq_u32 s53, 12
	s_cselect_b32 s19, s7, s17
	s_cselect_b32 s18, s49, s16
	s_cselect_b32 s17, s5, s52
	s_cselect_b32 s16, s50, s51
	s_mov_b32 m0, s43
	ds_read_b128 v[214:217], v165
	ds_read_b128 v[218:221], v165 offset:1024
	ds_read_b128 v[222:225], v165 offset:2048
	ds_read_b128 v[226:229], v165 offset:3072
	ds_read_b128 v[230:233], v165 offset:4096
	ds_read_b128 v[234:237], v165 offset:5120
	ds_read_b128 v[238:241], v165 offset:6144
	ds_read_b128 v[242:245], v165 offset:7168
	global_load_lds_dwordx4 v136, s[14:15]
	s_mov_b32 m0, s44
	s_nop 0
	global_load_lds_dwordx4 v138, s[14:15]
	s_waitcnt vmcnt(8)
	s_waitcnt lgkmcnt(0)
	s_barrier
	s_setprio 1
	v_mfma_f32_16x16x32_bf16 v[124:127], v[140:143], v[214:217], 0
	v_mfma_f32_16x16x32_bf16 v[124:127], v[168:171], v[218:221], v[124:127]
	v_mfma_f32_16x16x32_bf16 v[108:111], v[140:143], v[222:225], 0
	v_mfma_f32_16x16x32_bf16 v[108:111], v[168:171], v[226:229], v[108:111]
	v_mfma_f32_16x16x32_bf16 v[92:95], v[140:143], v[230:233], 0
	v_mfma_f32_16x16x32_bf16 v[92:95], v[168:171], v[234:237], v[92:95]
	v_mfma_f32_16x16x32_bf16 v[76:79], v[140:143], v[238:241], 0
	v_mfma_f32_16x16x32_bf16 v[76:79], v[168:171], v[242:245], v[76:79]
	v_mfma_f32_16x16x32_bf16 v[116:119], v[172:175], v[214:217], 0
	v_mfma_f32_16x16x32_bf16 v[116:119], v[176:179], v[218:221], v[116:119]
	v_mfma_f32_16x16x32_bf16 v[100:103], v[172:175], v[222:225], 0
	v_mfma_f32_16x16x32_bf16 v[100:103], v[176:179], v[226:229], v[100:103]
	v_mfma_f32_16x16x32_bf16 v[84:87], v[172:175], v[230:233], 0
	v_mfma_f32_16x16x32_bf16 v[84:87], v[176:179], v[234:237], v[84:87]
	v_mfma_f32_16x16x32_bf16 v[68:71], v[172:175], v[238:241], 0
	v_mfma_f32_16x16x32_bf16 v[68:71], v[176:179], v[242:245], v[68:71]
	v_mfma_f32_16x16x32_bf16 v[120:123], v[180:183], v[214:217], 0
	v_mfma_f32_16x16x32_bf16 v[120:123], v[184:187], v[218:221], v[120:123]
	v_mfma_f32_16x16x32_bf16 v[104:107], v[180:183], v[222:225], 0
	v_mfma_f32_16x16x32_bf16 v[104:107], v[184:187], v[226:229], v[104:107]
	v_mfma_f32_16x16x32_bf16 v[88:91], v[180:183], v[230:233], 0
	v_mfma_f32_16x16x32_bf16 v[88:91], v[184:187], v[234:237], v[88:91]
	v_mfma_f32_16x16x32_bf16 v[72:75], v[180:183], v[238:241], 0
	v_mfma_f32_16x16x32_bf16 v[72:75], v[184:187], v[242:245], v[72:75]
	v_mfma_f32_16x16x32_bf16 v[112:115], v[188:191], v[214:217], 0
	ds_read_b128 v[214:217], v165 offset:16384
	v_mfma_f32_16x16x32_bf16 v[112:115], v[210:213], v[218:221], v[112:115]
	ds_read_b128 v[218:221], v165 offset:17408
	v_mfma_f32_16x16x32_bf16 v[96:99], v[188:191], v[222:225], 0
	ds_read_b128 v[222:225], v165 offset:18432
	v_mfma_f32_16x16x32_bf16 v[96:99], v[210:213], v[226:229], v[96:99]
	ds_read_b128 v[226:229], v165 offset:19456
	v_mfma_f32_16x16x32_bf16 v[80:83], v[188:191], v[230:233], 0
	ds_read_b128 v[230:233], v165 offset:20480
	v_mfma_f32_16x16x32_bf16 v[80:83], v[210:213], v[234:237], v[80:83]
	ds_read_b128 v[234:237], v165 offset:21504
	v_mfma_f32_16x16x32_bf16 v[64:67], v[188:191], v[238:241], 0
	ds_read_b128 v[238:241], v165 offset:22528
	v_mfma_f32_16x16x32_bf16 v[64:67], v[210:213], v[242:245], v[64:67]
	ds_read_b128 v[242:245], v165 offset:23552
	s_setprio 0
	s_barrier
	s_mov_b32 m0, s27
	s_add_u32 s54, s16, 0x40000
	s_addc_u32 s55, s17, 0
	global_load_lds_dwordx4 v132, s[16:17]
	s_mov_b32 m0, s28
	s_nop 0
	global_load_lds_dwordx4 v128, s[16:17]
	s_mov_b32 m0, s29
	s_nop 0
	global_load_lds_dwordx4 v132, s[54:55]
	s_mov_b32 m0, s30
	s_nop 0
	global_load_lds_dwordx4 v128, s[54:55]
	s_mov_b32 m0, s22
	s_nop 0
	global_load_lds_dwordx4 v134, s[18:19]
	s_mov_b32 m0, s31
	s_nop 0
	global_load_lds_dwordx4 v130, s[18:19]
	s_waitcnt vmcnt(8)
	s_waitcnt lgkmcnt(0)
	s_barrier
	s_setprio 1
	v_mfma_f32_16x16x32_bf16 v[60:63], v[140:143], v[214:217], 0
	v_mfma_f32_16x16x32_bf16 v[60:63], v[168:171], v[218:221], v[60:63]
	v_mfma_f32_16x16x32_bf16 v[44:47], v[140:143], v[222:225], 0
	v_mfma_f32_16x16x32_bf16 v[44:47], v[168:171], v[226:229], v[44:47]
	v_mfma_f32_16x16x32_bf16 v[28:31], v[140:143], v[230:233], 0
	v_mfma_f32_16x16x32_bf16 v[28:31], v[168:171], v[234:237], v[28:31]
	v_mfma_f32_16x16x32_bf16 v[12:15], v[140:143], v[238:241], 0
	ds_read_b128 v[140:143], v254 offset:32768
	v_mfma_f32_16x16x32_bf16 v[12:15], v[168:171], v[242:245], v[12:15]
	ds_read_b128 v[168:171], v254 offset:33792
	v_mfma_f32_16x16x32_bf16 v[52:55], v[172:175], v[214:217], 0
	v_mfma_f32_16x16x32_bf16 v[52:55], v[176:179], v[218:221], v[52:55]
	v_mfma_f32_16x16x32_bf16 v[36:39], v[172:175], v[222:225], 0
	v_mfma_f32_16x16x32_bf16 v[36:39], v[176:179], v[226:229], v[36:39]
	v_mfma_f32_16x16x32_bf16 v[20:23], v[172:175], v[230:233], 0
	v_mfma_f32_16x16x32_bf16 v[20:23], v[176:179], v[234:237], v[20:23]
	v_mfma_f32_16x16x32_bf16 v[4:7], v[172:175], v[238:241], 0
	ds_read_b128 v[172:175], v254 offset:34816
	v_mfma_f32_16x16x32_bf16 v[4:7], v[176:179], v[242:245], v[4:7]
	ds_read_b128 v[176:179], v254 offset:35840
	v_mfma_f32_16x16x32_bf16 v[56:59], v[180:183], v[214:217], 0
	v_mfma_f32_16x16x32_bf16 v[56:59], v[184:187], v[218:221], v[56:59]
	v_mfma_f32_16x16x32_bf16 v[40:43], v[180:183], v[222:225], 0
	v_mfma_f32_16x16x32_bf16 v[40:43], v[184:187], v[226:229], v[40:43]
	v_mfma_f32_16x16x32_bf16 v[24:27], v[180:183], v[230:233], 0
	v_mfma_f32_16x16x32_bf16 v[24:27], v[184:187], v[234:237], v[24:27]
	v_mfma_f32_16x16x32_bf16 v[8:11], v[180:183], v[238:241], 0
	ds_read_b128 v[180:183], v254 offset:49152
	v_mfma_f32_16x16x32_bf16 v[8:11], v[184:187], v[242:245], v[8:11]
	ds_read_b128 v[184:187], v254 offset:50176
	v_mfma_f32_16x16x32_bf16 v[48:51], v[188:191], v[214:217], 0
	ds_read_b128 v[214:217], v165 offset:32768
	v_mfma_f32_16x16x32_bf16 v[48:51], v[210:213], v[218:221], v[48:51]
	ds_read_b128 v[218:221], v165 offset:33792
	v_mfma_f32_16x16x32_bf16 v[32:35], v[188:191], v[222:225], 0
	ds_read_b128 v[222:225], v165 offset:34816
	v_mfma_f32_16x16x32_bf16 v[32:35], v[210:213], v[226:229], v[32:35]
	ds_read_b128 v[226:229], v165 offset:35840
	v_mfma_f32_16x16x32_bf16 v[16:19], v[188:191], v[230:233], 0
	ds_read_b128 v[230:233], v165 offset:36864
	v_mfma_f32_16x16x32_bf16 v[16:19], v[210:213], v[234:237], v[16:19]
	ds_read_b128 v[234:237], v165 offset:37888
	v_mfma_f32_16x16x32_bf16 v[0:3], v[188:191], v[238:241], 0
	ds_read_b128 v[188:191], v254 offset:51200
	ds_read_b128 v[238:241], v165 offset:38912
	v_mfma_f32_16x16x32_bf16 v[0:3], v[210:213], v[242:245], v[0:3]
	ds_read_b128 v[210:213], v254 offset:52224
	ds_read_b128 v[242:245], v165 offset:39936
	s_setprio 0
	s_barrier
; #define PG8_STAGE(bufoff, gbase, voff) do { _Pragma("unroll") for (int _i = 0; _i < 2; ++_i) \
;         __builtin_amdgcn_global_load_lds((const unsigned*)((const char*)(gbase) + (voff)[_i]), (PG8_LAS unsigned*)(lds + (bufoff) + ldsw + _i * 8192), 16, 0, 0); } while (0)
; #define PG8_LDA(dst, b, h) do { _Pragma("unroll") for (int m = 0; m < 4; ++m) _Pragma("unroll") for (int k = 0; k < 2; ++k) dst[m][k] = *(const PG8_LAS bf16x8*)(lds + PG8_SA(b, h) + aoff + m * 2048 + k * 1024); } while (0)
; #define PG8_LDB(dst, b, h) do { _Pragma("unroll") for (int n = 0; n < 2; ++n) _Pragma("unroll") for (int k = 0; k < 2; ++k) dst[n][k] = *(const PG8_LAS bf16x8*)(lds + PG8_SB(b, h) + boff + n * 2048 + k * 1024); } while (0)
; #define PG8_MMA(ai, bj, At, Bt) do { __builtin_amdgcn_s_setprio(1); _Pragma("unroll") for (int m = 0; m < 4; ++m) _Pragma("unroll") for (int n = 0; n < 2; ++n) _Pragma("unroll") for (int k = 0; k < 2; ++k) \
;         acc[ai][bj][m][n] = __builtin_amdgcn_mfma_f32_16x16x32_bf16(Bt[n][k], At[m][k], acc[ai][bj][m][n], 0, 0, 0); __builtin_amdgcn_s_setprio(0); } while (0)
; #define PG8_WAIT_V(n) asm volatile("s_waitcnt vmcnt(" #n ")" ::: "memory")
; #define PG8_WAIT_L(n) asm volatile("s_waitcnt lgkmcnt(" #n ")" ::: "memory")
; #define PG8_BAR __builtin_amdgcn_s_barrier()
; #define PG8_SCHED __builtin_amdgcn_sched_barrier(0)
; template <class Epi, class Sched, bool ALIGN_EPI = false, bool SP2 = false>
; __device__ __forceinline__ void gemm_phase(PG8_LAS unsigned char* lds, const Gemm g, const Sched& S, const Epi& E) {
;     ...
;         for (int t = 0; t < nt; t += 2) {
;     ...
;             PG8_LDB(B0, 1, 0); PG8_LDB(B1, 1, 1); PG8_SCHED; PG8_LDA(At, 1, 0); PG8_STAGE(PG8_SA(0, 1), a2 + hstep, voffA);
;             PG8_WAIT_V(8); PG8_WAIT_L(0); PG8_BAR; PG8_MMA(0, 0, At, B0); PG8_MMA(0, 1, At, B1); PG8_BAR; PG8_SCHED;
;             PG8_LDA(At, 1, 1); PG8_STAGE(PG8_SB(1, 0), b3, voffB); PG8_STAGE(PG8_SB(1, 1), b3 + hstep, voffB); PG8_STAGE(PG8_SA(1, 0), a3, voffA);
;             PG8_WAIT_V(8); PG8_WAIT_L(0); PG8_BAR; PG8_MMA(1, 0, At, B0); PG8_MMA(1, 1, At, B1); PG8_BAR; PG8_SCHED;
	s_add_u32 s18, s18, 0x40000
	s_addc_u32 s19, s19, 0
	s_mov_b32 m0, s33
	global_load_lds_dwordx4 v134, s[18:19]
	s_mov_b32 m0, s34
	s_nop 0
	global_load_lds_dwordx4 v130, s[18:19]
	s_waitcnt vmcnt(8)
	s_waitcnt lgkmcnt(0)
	s_barrier
	s_setprio 1
	v_mfma_f32_16x16x32_bf16 v[124:127], v[140:143], v[214:217], v[124:127]
	v_mfma_f32_16x16x32_bf16 v[124:127], v[168:171], v[218:221], v[124:127]
	v_mfma_f32_16x16x32_bf16 v[108:111], v[140:143], v[222:225], v[108:111]
	v_mfma_f32_16x16x32_bf16 v[108:111], v[168:171], v[226:229], v[108:111]
	v_mfma_f32_16x16x32_bf16 v[92:95], v[140:143], v[230:233], v[92:95]
	v_mfma_f32_16x16x32_bf16 v[92:95], v[168:171], v[234:237], v[92:95]
	v_mfma_f32_16x16x32_bf16 v[76:79], v[140:143], v[238:241], v[76:79]
	v_mfma_f32_16x16x32_bf16 v[76:79], v[168:171], v[242:245], v[76:79]
	v_mfma_f32_16x16x32_bf16 v[116:119], v[172:175], v[214:217], v[116:119]
	v_mfma_f32_16x16x32_bf16 v[116:119], v[176:179], v[218:221], v[116:119]
	v_mfma_f32_16x16x32_bf16 v[100:103], v[172:175], v[222:225], v[100:103]
	v_mfma_f32_16x16x32_bf16 v[100:103], v[176:179], v[226:229], v[100:103]
	v_mfma_f32_16x16x32_bf16 v[84:87], v[172:175], v[230:233], v[84:87]
	v_mfma_f32_16x16x32_bf16 v[84:87], v[176:179], v[234:237], v[84:87]
	v_mfma_f32_16x16x32_bf16 v[68:71], v[172:175], v[238:241], v[68:71]
	v_mfma_f32_16x16x32_bf16 v[68:71], v[176:179], v[242:245], v[68:71]
	v_mfma_f32_16x16x32_bf16 v[120:123], v[180:183], v[214:217], v[120:123]
	v_mfma_f32_16x16x32_bf16 v[120:123], v[184:187], v[218:221], v[120:123]
	v_mfma_f32_16x16x32_bf16 v[104:107], v[180:183], v[222:225], v[104:107]
	v_mfma_f32_16x16x32_bf16 v[104:107], v[184:187], v[226:229], v[104:107]
	v_mfma_f32_16x16x32_bf16 v[88:91], v[180:183], v[230:233], v[88:91]
	v_mfma_f32_16x16x32_bf16 v[88:91], v[184:187], v[234:237], v[88:91]
	v_mfma_f32_16x16x32_bf16 v[72:75], v[180:183], v[238:241], v[72:75]
	v_mfma_f32_16x16x32_bf16 v[72:75], v[184:187], v[242:245], v[72:75]
	v_mfma_f32_16x16x32_bf16 v[112:115], v[188:191], v[214:217], v[112:115]
	ds_read_b128 v[214:217], v165 offset:49152
	v_mfma_f32_16x16x32_bf16 v[112:115], v[210:213], v[218:221], v[112:115]
	ds_read_b128 v[218:221], v165 offset:50176
	v_mfma_f32_16x16x32_bf16 v[96:99], v[188:191], v[222:225], v[96:99]
	ds_read_b128 v[222:225], v165 offset:51200
	v_mfma_f32_16x16x32_bf16 v[96:99], v[210:213], v[226:229], v[96:99]
	ds_read_b128 v[226:229], v165 offset:52224
	v_mfma_f32_16x16x32_bf16 v[80:83], v[188:191], v[230:233], v[80:83]
	ds_read_b128 v[230:233], v165 offset:53248
	v_mfma_f32_16x16x32_bf16 v[80:83], v[210:213], v[234:237], v[80:83]
	ds_read_b128 v[234:237], v165 offset:54272
	v_mfma_f32_16x16x32_bf16 v[64:67], v[188:191], v[238:241], v[64:67]
	ds_read_b128 v[238:241], v165 offset:55296
	v_mfma_f32_16x16x32_bf16 v[64:67], v[210:213], v[242:245], v[64:67]
	ds_read_b128 v[242:245], v165 offset:56320
	s_setprio 0
	s_barrier
	s_mov_b32 m0, s37
	s_add_u32 s16, s16, 0x40080
	s_addc_u32 s17, s17, 0
	s_add_u32 s98, s16, 0xfffc0000
	s_addc_u32 s99, s17, -1
	global_load_lds_dwordx4 v132, s[98:99]
	s_mov_b32 m0, s38
	s_nop 0
	global_load_lds_dwordx4 v128, s[98:99]
	s_mov_b32 m0, s41
	s_nop 0
	global_load_lds_dwordx4 v132, s[16:17]
	s_mov_b32 m0, s42
	s_nop 0
	global_load_lds_dwordx4 v128, s[16:17]
	s_mov_b32 m0, s39
	s_nop 0
	s_add_u32 s100, s18, 0xfffc0080
	s_addc_u32 s101, s19, -1
	global_load_lds_dwordx4 v134, s[100:101]
	s_mov_b32 m0, s40
	s_nop 0
	global_load_lds_dwordx4 v130, s[100:101]
	s_waitcnt vmcnt(8)
	s_waitcnt lgkmcnt(0)
	s_barrier
	s_setprio 1
	v_mfma_f32_16x16x32_bf16 v[60:63], v[140:143], v[214:217], v[60:63]
	v_mfma_f32_16x16x32_bf16 v[60:63], v[168:171], v[218:221], v[60:63]
	v_mfma_f32_16x16x32_bf16 v[44:47], v[140:143], v[222:225], v[44:47]
	v_mfma_f32_16x16x32_bf16 v[44:47], v[168:171], v[226:229], v[44:47]
	v_mfma_f32_16x16x32_bf16 v[28:31], v[140:143], v[230:233], v[28:31]
	v_mfma_f32_16x16x32_bf16 v[28:31], v[168:171], v[234:237], v[28:31]
	v_mfma_f32_16x16x32_bf16 v[12:15], v[140:143], v[238:241], v[12:15]
	ds_read_b128 v[140:143], v254
	v_mfma_f32_16x16x32_bf16 v[12:15], v[168:171], v[242:245], v[12:15]
	ds_read_b128 v[168:171], v254 offset:1024
	v_mfma_f32_16x16x32_bf16 v[52:55], v[172:175], v[214:217], v[52:55]
	v_mfma_f32_16x16x32_bf16 v[52:55], v[176:179], v[218:221], v[52:55]
	v_mfma_f32_16x16x32_bf16 v[36:39], v[172:175], v[222:225], v[36:39]
	v_mfma_f32_16x16x32_bf16 v[36:39], v[176:179], v[226:229], v[36:39]
	v_mfma_f32_16x16x32_bf16 v[20:23], v[172:175], v[230:233], v[20:23]
	v_mfma_f32_16x16x32_bf16 v[20:23], v[176:179], v[234:237], v[20:23]
	v_mfma_f32_16x16x32_bf16 v[4:7], v[172:175], v[238:241], v[4:7]
	ds_read_b128 v[172:175], v254 offset:2048
	v_mfma_f32_16x16x32_bf16 v[4:7], v[176:179], v[242:245], v[4:7]
	ds_read_b128 v[176:179], v254 offset:3072
	v_mfma_f32_16x16x32_bf16 v[56:59], v[180:183], v[214:217], v[56:59]
	v_mfma_f32_16x16x32_bf16 v[56:59], v[184:187], v[218:221], v[56:59]
	v_mfma_f32_16x16x32_bf16 v[40:43], v[180:183], v[222:225], v[40:43]
	v_mfma_f32_16x16x32_bf16 v[40:43], v[184:187], v[226:229], v[40:43]
	v_mfma_f32_16x16x32_bf16 v[24:27], v[180:183], v[230:233], v[24:27]
	v_mfma_f32_16x16x32_bf16 v[24:27], v[184:187], v[234:237], v[24:27]
	v_mfma_f32_16x16x32_bf16 v[8:11], v[180:183], v[238:241], v[8:11]
	ds_read_b128 v[180:183], v254 offset:16384
	v_mfma_f32_16x16x32_bf16 v[8:11], v[184:187], v[242:245], v[8:11]
	ds_read_b128 v[184:187], v254 offset:17408
	v_mfma_f32_16x16x32_bf16 v[48:51], v[188:191], v[214:217], v[48:51]
	ds_read_b128 v[214:217], v165
	v_mfma_f32_16x16x32_bf16 v[48:51], v[210:213], v[218:221], v[48:51]
	ds_read_b128 v[218:221], v165 offset:1024
	v_mfma_f32_16x16x32_bf16 v[32:35], v[188:191], v[222:225], v[32:35]
	ds_read_b128 v[222:225], v165 offset:2048
	v_mfma_f32_16x16x32_bf16 v[32:35], v[210:213], v[226:229], v[32:35]
	ds_read_b128 v[226:229], v165 offset:3072
	v_mfma_f32_16x16x32_bf16 v[16:19], v[188:191], v[230:233], v[16:19]
	ds_read_b128 v[230:233], v165 offset:4096
	v_mfma_f32_16x16x32_bf16 v[16:19], v[210:213], v[234:237], v[16:19]
	ds_read_b128 v[234:237], v165 offset:5120
	v_mfma_f32_16x16x32_bf16 v[0:3], v[188:191], v[238:241], v[0:3]
	ds_read_b128 v[188:191], v254 offset:18432
	ds_read_b128 v[238:241], v165 offset:6144
	v_mfma_f32_16x16x32_bf16 v[0:3], v[210:213], v[242:245], v[0:3]
	ds_read_b128 v[210:213], v254 offset:19456
	ds_read_b128 v[242:245], v165 offset:7168
	s_setprio 0
	s_barrier
	s_add_i32 s53, s53, 2
	s_add_u32 s14, s14, 0x100
	s_addc_u32 s15, s15, 0
	s_add_u32 s51, s51, 0x100
	s_addc_u32 s52, s52, 0
	s_cmp_gt_u32 s53, 13
; #define PG8_STAGE(bufoff, gbase, voff) do { _Pragma("unroll") for (int _i = 0; _i < 2; ++_i) \
;         __builtin_amdgcn_global_load_lds((const unsigned*)((const char*)(gbase) + (voff)[_i]), (PG8_LAS unsigned*)(lds + (bufoff) + ldsw + _i * 8192), 16, 0, 0); } while (0)
; #define PG8_LDA(dst, b, h) do { _Pragma("unroll") for (int m = 0; m < 4; ++m) _Pragma("unroll") for (int k = 0; k < 2; ++k) dst[m][k] = *(const PG8_LAS bf16x8*)(lds + PG8_SA(b, h) + aoff + m * 2048 + k * 1024); } while (0)
; #define PG8_LDB(dst, b, h) do { _Pragma("unroll") for (int n = 0; n < 2; ++n) _Pragma("unroll") for (int k = 0; k < 2; ++k) dst[n][k] = *(const PG8_LAS bf16x8*)(lds + PG8_SB(b, h) + boff + n * 2048 + k * 1024); } while (0)
; #define PG8_WAIT_V(n) asm volatile("s_waitcnt vmcnt(" #n ")" ::: "memory")
; #define PG8_WAIT_L(n) asm volatile("s_waitcnt lgkmcnt(" #n ")" ::: "memory")
; #define PG8_BAR __builtin_amdgcn_s_barrier()
; #define PG8_SCHED __builtin_amdgcn_sched_barrier(0)
; template <class Epi, class Sched, bool ALIGN_EPI = false, bool SP2 = false>
; __device__ __forceinline__ void gemm_phase(PG8_LAS unsigned char* lds, const Gemm g, const Sched& S, const Epi& E) {
;     ...
;             const char* a1 = cA + (size_t)(t + 1) * kstep;
;             const char* a2 = last ? nA : cA + (size_t)(t + 2) * kstep; const char* b2 = last ? nB : cB + (size_t)(t + 2) * kstep;
;             const char* a3 = a2 + kstep; const char* b3 = b2 + kstep;
;             if (last && has_next) S.a_ready(nxt);
;             if constexpr (SP2) {
;             PG8_LDB(B0, 0, 0); PG8_LDB(B1, 0, 1); PG8_SCHED; PG8_LDA(At, 0, 0); PG8_STAGE(PG8_SA(1, 1), a1 + hstep, voffA);
;             PG8_WAIT_V(8); PG8_WAIT_L(0); PG8_BAR; PG8_MMA(0, 0, At, B0); PG8_MMA(0, 1, At, B1); PG8_BAR; PG8_SCHED;
;             PG8_LDA(At, 0, 1); PG8_STAGE(PG8_SB(0, 0), b2, voffB); PG8_STAGE(PG8_SB(0, 1), b2 + hstep, voffB); PG8_STAGE(PG8_SA(0, 0), a2, voffA);
;             PG8_WAIT_V(8); PG8_WAIT_L(0); PG8_BAR; PG8_MMA(1, 0, At, B0); PG8_MMA(1, 1, At, B1); PG8_BAR; PG8_SCHED;
;             PG8_LDB(B0, 1, 0); PG8_LDB(B1, 1, 1); PG8_SCHED; PG8_LDA(At, 1, 0); PG8_STAGE(PG8_SA(0, 1), a2 + hstep, voffA);
;             PG8_WAIT_V(8); PG8_WAIT_L(0); PG8_BAR; PG8_MMA(0, 0, At, B0); PG8_MMA(0, 1, At, B1); PG8_BAR; PG8_SCHED;
.Lup_loop_w1:
	s_add_u32 s16, s14, 0xfffc0080
	s_addc_u32 s17, s15, -1
	s_cmp_eq_u32 s53, 12
	s_cselect_b32 s19, s7, s17
	s_cselect_b32 s18, s49, s16
	s_cselect_b32 s17, s5, s52
	s_cselect_b32 s16, s50, s51
	s_mov_b32 m0, s43
	global_load_lds_dwordx4 v136, s[14:15]
	s_mov_b32 m0, s44
	s_nop 0
	global_load_lds_dwordx4 v138, s[14:15]
	s_waitcnt vmcnt(8)
	s_waitcnt lgkmcnt(0)
	s_barrier
	s_setprio 1
	v_mfma_f32_16x16x32_bf16 v[124:127], v[140:143], v[214:217], v[124:127]
	v_mfma_f32_16x16x32_bf16 v[124:127], v[168:171], v[218:221], v[124:127]
	v_mfma_f32_16x16x32_bf16 v[108:111], v[140:143], v[222:225], v[108:111]
	v_mfma_f32_16x16x32_bf16 v[108:111], v[168:171], v[226:229], v[108:111]
	v_mfma_f32_16x16x32_bf16 v[92:95], v[140:143], v[230:233], v[92:95]
	v_mfma_f32_16x16x32_bf16 v[92:95], v[168:171], v[234:237], v[92:95]
	v_mfma_f32_16x16x32_bf16 v[76:79], v[140:143], v[238:241], v[76:79]
	v_mfma_f32_16x16x32_bf16 v[76:79], v[168:171], v[242:245], v[76:79]
	v_mfma_f32_16x16x32_bf16 v[116:119], v[172:175], v[214:217], v[116:119]
	v_mfma_f32_16x16x32_bf16 v[116:119], v[176:179], v[218:221], v[116:119]
	v_mfma_f32_16x16x32_bf16 v[100:103], v[172:175], v[222:225], v[100:103]
	v_mfma_f32_16x16x32_bf16 v[100:103], v[176:179], v[226:229], v[100:103]
	v_mfma_f32_16x16x32_bf16 v[84:87], v[172:175], v[230:233], v[84:87]
	v_mfma_f32_16x16x32_bf16 v[84:87], v[176:179], v[234:237], v[84:87]
	v_mfma_f32_16x16x32_bf16 v[68:71], v[172:175], v[238:241], v[68:71]
	v_mfma_f32_16x16x32_bf16 v[68:71], v[176:179], v[242:245], v[68:71]
	v_mfma_f32_16x16x32_bf16 v[120:123], v[180:183], v[214:217], v[120:123]
	v_mfma_f32_16x16x32_bf16 v[120:123], v[184:187], v[218:221], v[120:123]
	v_mfma_f32_16x16x32_bf16 v[104:107], v[180:183], v[222:225], v[104:107]
	v_mfma_f32_16x16x32_bf16 v[104:107], v[184:187], v[226:229], v[104:107]
	v_mfma_f32_16x16x32_bf16 v[88:91], v[180:183], v[230:233], v[88:91]
	v_mfma_f32_16x16x32_bf16 v[88:91], v[184:187], v[234:237], v[88:91]
	v_mfma_f32_16x16x32_bf16 v[72:75], v[180:183], v[238:241], v[72:75]
	v_mfma_f32_16x16x32_bf16 v[72:75], v[184:187], v[242:245], v[72:75]
	v_mfma_f32_16x16x32_bf16 v[112:115], v[188:191], v[214:217], v[112:115]
	ds_read_b128 v[214:217], v165 offset:16384
	v_mfma_f32_16x16x32_bf16 v[112:115], v[210:213], v[218:221], v[112:115]
	ds_read_b128 v[218:221], v165 offset:17408
	v_mfma_f32_16x16x32_bf16 v[96:99], v[188:191], v[222:225], v[96:99]
	ds_read_b128 v[222:225], v165 offset:18432
	v_mfma_f32_16x16x32_bf16 v[96:99], v[210:213], v[226:229], v[96:99]
	ds_read_b128 v[226:229], v165 offset:19456
	v_mfma_f32_16x16x32_bf16 v[80:83], v[188:191], v[230:233], v[80:83]
	ds_read_b128 v[230:233], v165 offset:20480
	v_mfma_f32_16x16x32_bf16 v[80:83], v[210:213], v[234:237], v[80:83]
	ds_read_b128 v[234:237], v165 offset:21504
	v_mfma_f32_16x16x32_bf16 v[64:67], v[188:191], v[238:241], v[64:67]
	ds_read_b128 v[238:241], v165 offset:22528
	v_mfma_f32_16x16x32_bf16 v[64:67], v[210:213], v[242:245], v[64:67]
	ds_read_b128 v[242:245], v165 offset:23552
	s_setprio 0
	s_barrier
	s_mov_b32 m0, s27
	s_add_u32 s54, s16, 0x40000
	s_addc_u32 s55, s17, 0
	global_load_lds_dwordx4 v132, s[16:17]
	s_mov_b32 m0, s28
	s_nop 0
	global_load_lds_dwordx4 v128, s[16:17]
	s_mov_b32 m0, s29
	s_nop 0
	global_load_lds_dwordx4 v132, s[54:55]
	s_mov_b32 m0, s30
	s_nop 0
	global_load_lds_dwordx4 v128, s[54:55]
	s_mov_b32 m0, s22
	s_nop 0
	global_load_lds_dwordx4 v134, s[18:19]
	s_mov_b32 m0, s31
	s_nop 0
	global_load_lds_dwordx4 v130, s[18:19]
	s_waitcnt vmcnt(8)
	s_waitcnt lgkmcnt(0)
	s_barrier
	s_setprio 1
	v_mfma_f32_16x16x32_bf16 v[60:63], v[140:143], v[214:217], v[60:63]
	v_mfma_f32_16x16x32_bf16 v[60:63], v[168:171], v[218:221], v[60:63]
	v_mfma_f32_16x16x32_bf16 v[44:47], v[140:143], v[222:225], v[44:47]
	v_mfma_f32_16x16x32_bf16 v[44:47], v[168:171], v[226:229], v[44:47]
	v_mfma_f32_16x16x32_bf16 v[28:31], v[140:143], v[230:233], v[28:31]
	v_mfma_f32_16x16x32_bf16 v[28:31], v[168:171], v[234:237], v[28:31]
	v_mfma_f32_16x16x32_bf16 v[12:15], v[140:143], v[238:241], v[12:15]
	ds_read_b128 v[140:143], v254 offset:32768
	v_mfma_f32_16x16x32_bf16 v[12:15], v[168:171], v[242:245], v[12:15]
	ds_read_b128 v[168:171], v254 offset:33792
	v_mfma_f32_16x16x32_bf16 v[52:55], v[172:175], v[214:217], v[52:55]
	v_mfma_f32_16x16x32_bf16 v[52:55], v[176:179], v[218:221], v[52:55]
	v_mfma_f32_16x16x32_bf16 v[36:39], v[172:175], v[222:225], v[36:39]
	v_mfma_f32_16x16x32_bf16 v[36:39], v[176:179], v[226:229], v[36:39]
	v_mfma_f32_16x16x32_bf16 v[20:23], v[172:175], v[230:233], v[20:23]
	v_mfma_f32_16x16x32_bf16 v[20:23], v[176:179], v[234:237], v[20:23]
	v_mfma_f32_16x16x32_bf16 v[4:7], v[172:175], v[238:241], v[4:7]
	ds_read_b128 v[172:175], v254 offset:34816
	v_mfma_f32_16x16x32_bf16 v[4:7], v[176:179], v[242:245], v[4:7]
	ds_read_b128 v[176:179], v254 offset:35840
	v_mfma_f32_16x16x32_bf16 v[56:59], v[180:183], v[214:217], v[56:59]
	v_mfma_f32_16x16x32_bf16 v[56:59], v[184:187], v[218:221], v[56:59]
	v_mfma_f32_16x16x32_bf16 v[40:43], v[180:183], v[222:225], v[40:43]
	v_mfma_f32_16x16x32_bf16 v[40:43], v[184:187], v[226:229], v[40:43]
	v_mfma_f32_16x16x32_bf16 v[24:27], v[180:183], v[230:233], v[24:27]
	v_mfma_f32_16x16x32_bf16 v[24:27], v[184:187], v[234:237], v[24:27]
	v_mfma_f32_16x16x32_bf16 v[8:11], v[180:183], v[238:241], v[8:11]
	ds_read_b128 v[180:183], v254 offset:49152
	v_mfma_f32_16x16x32_bf16 v[8:11], v[184:187], v[242:245], v[8:11]
	ds_read_b128 v[184:187], v254 offset:50176
	v_mfma_f32_16x16x32_bf16 v[48:51], v[188:191], v[214:217], v[48:51]
	ds_read_b128 v[214:217], v165 offset:32768
	v_mfma_f32_16x16x32_bf16 v[48:51], v[210:213], v[218:221], v[48:51]
	ds_read_b128 v[218:221], v165 offset:33792
	v_mfma_f32_16x16x32_bf16 v[32:35], v[188:191], v[222:225], v[32:35]
	ds_read_b128 v[222:225], v165 offset:34816
	v_mfma_f32_16x16x32_bf16 v[32:35], v[210:213], v[226:229], v[32:35]
	ds_read_b128 v[226:229], v165 offset:35840
	v_mfma_f32_16x16x32_bf16 v[16:19], v[188:191], v[230:233], v[16:19]
	ds_read_b128 v[230:233], v165 offset:36864
	v_mfma_f32_16x16x32_bf16 v[16:19], v[210:213], v[234:237], v[16:19]
	ds_read_b128 v[234:237], v165 offset:37888
	v_mfma_f32_16x16x32_bf16 v[0:3], v[188:191], v[238:241], v[0:3]
	ds_read_b128 v[188:191], v254 offset:51200
	ds_read_b128 v[238:241], v165 offset:38912
	v_mfma_f32_16x16x32_bf16 v[0:3], v[210:213], v[242:245], v[0:3]
	ds_read_b128 v[210:213], v254 offset:52224
	ds_read_b128 v[242:245], v165 offset:39936
	s_setprio 0
	s_barrier
; #define PG8_STAGE(bufoff, gbase, voff) do { _Pragma("unroll") for (int _i = 0; _i < 2; ++_i) \
;         __builtin_amdgcn_global_load_lds((const unsigned*)((const char*)(gbase) + (voff)[_i]), (PG8_LAS unsigned*)(lds + (bufoff) + ldsw + _i * 8192), 16, 0, 0); } while (0)
; #define PG8_LDA(dst, b, h) do { _Pragma("unroll") for (int m = 0; m < 4; ++m) _Pragma("unroll") for (int k = 0; k < 2; ++k) dst[m][k] = *(const PG8_LAS bf16x8*)(lds + PG8_SA(b, h) + aoff + m * 2048 + k * 1024); } while (0)
; #define PG8_LDB(dst, b, h) do { _Pragma("unroll") for (int n = 0; n < 2; ++n) _Pragma("unroll") for (int k = 0; k < 2; ++k) dst[n][k] = *(const PG8_LAS bf16x8*)(lds + PG8_SB(b, h) + boff + n * 2048 + k * 1024); } while (0)
; #define PG8_MMA(ai, bj, At, Bt) do { __builtin_amdgcn_s_setprio(1); _Pragma("unroll") for (int m = 0; m < 4; ++m) _Pragma("unroll") for (int n = 0; n < 2; ++n) _Pragma("unroll") for (int k = 0; k < 2; ++k) \
;         acc[ai][bj][m][n] = __builtin_amdgcn_mfma_f32_16x16x32_bf16(Bt[n][k], At[m][k], acc[ai][bj][m][n], 0, 0, 0); __builtin_amdgcn_s_setprio(0); } while (0)
; #define PG8_WAIT_V(n) asm volatile("s_waitcnt vmcnt(" #n ")" ::: "memory")
; #define PG8_WAIT_L(n) asm volatile("s_waitcnt lgkmcnt(" #n ")" ::: "memory")
; #define PG8_BAR __builtin_amdgcn_s_barrier()
; #define PG8_SCHED __builtin_amdgcn_sched_barrier(0)
; template <class Epi, class Sched, bool ALIGN_EPI = false, bool SP2 = false>
; __device__ __forceinline__ void gemm_phase(PG8_LAS unsigned char* lds, const Gemm g, const Sched& S, const Epi& E) {
;     ...
;         for (int t = 0; t < nt; t += 2) {
;             const bool last = (t == nt - 2);
;             const char* a1 = cA + (size_t)(t + 1) * kstep;
;             const char* a2 = last ? nA : cA + (size_t)(t + 2) * kstep; const char* b2 = last ? nB : cB + (size_t)(t + 2) * kstep;
;     ...
;             PG8_LDB(B0, 1, 0); PG8_LDB(B1, 1, 1); PG8_SCHED; PG8_LDA(At, 1, 0); PG8_STAGE(PG8_SA(0, 1), a2 + hstep, voffA);
;             PG8_WAIT_V(8); PG8_WAIT_L(0); PG8_BAR; PG8_MMA(0, 0, At, B0); PG8_MMA(0, 1, At, B1); PG8_BAR; PG8_SCHED;
;             PG8_LDA(At, 1, 1); PG8_STAGE(PG8_SB(1, 0), b3, voffB); PG8_STAGE(PG8_SB(1, 1), b3 + hstep, voffB); PG8_STAGE(PG8_SA(1, 0), a3, voffA);
;             PG8_WAIT_V(8); PG8_WAIT_L(0); PG8_BAR; PG8_MMA(1, 0, At, B0); PG8_MMA(1, 1, At, B1); PG8_BAR; PG8_SCHED;
	s_add_u32 s18, s18, 0x40000
	s_addc_u32 s19, s19, 0
	s_mov_b32 m0, s33
	global_load_lds_dwordx4 v134, s[18:19]
	s_mov_b32 m0, s34
	s_nop 0
	global_load_lds_dwordx4 v130, s[18:19]
	s_waitcnt vmcnt(8)
	s_waitcnt lgkmcnt(0)
	s_barrier
	s_setprio 1
	v_mfma_f32_16x16x32_bf16 v[124:127], v[140:143], v[214:217], v[124:127]
	v_mfma_f32_16x16x32_bf16 v[124:127], v[168:171], v[218:221], v[124:127]
	v_mfma_f32_16x16x32_bf16 v[108:111], v[140:143], v[222:225], v[108:111]
	v_mfma_f32_16x16x32_bf16 v[108:111], v[168:171], v[226:229], v[108:111]
	v_mfma_f32_16x16x32_bf16 v[92:95], v[140:143], v[230:233], v[92:95]
	v_mfma_f32_16x16x32_bf16 v[92:95], v[168:171], v[234:237], v[92:95]
	v_mfma_f32_16x16x32_bf16 v[76:79], v[140:143], v[238:241], v[76:79]
	v_mfma_f32_16x16x32_bf16 v[76:79], v[168:171], v[242:245], v[76:79]
	v_mfma_f32_16x16x32_bf16 v[116:119], v[172:175], v[214:217], v[116:119]
	v_mfma_f32_16x16x32_bf16 v[116:119], v[176:179], v[218:221], v[116:119]
	v_mfma_f32_16x16x32_bf16 v[100:103], v[172:175], v[222:225], v[100:103]
	v_mfma_f32_16x16x32_bf16 v[100:103], v[176:179], v[226:229], v[100:103]
	v_mfma_f32_16x16x32_bf16 v[84:87], v[172:175], v[230:233], v[84:87]
	v_mfma_f32_16x16x32_bf16 v[84:87], v[176:179], v[234:237], v[84:87]
	v_mfma_f32_16x16x32_bf16 v[68:71], v[172:175], v[238:241], v[68:71]
	v_mfma_f32_16x16x32_bf16 v[68:71], v[176:179], v[242:245], v[68:71]
	v_mfma_f32_16x16x32_bf16 v[120:123], v[180:183], v[214:217], v[120:123]
	v_mfma_f32_16x16x32_bf16 v[120:123], v[184:187], v[218:221], v[120:123]
	v_mfma_f32_16x16x32_bf16 v[104:107], v[180:183], v[222:225], v[104:107]
	v_mfma_f32_16x16x32_bf16 v[104:107], v[184:187], v[226:229], v[104:107]
	v_mfma_f32_16x16x32_bf16 v[88:91], v[180:183], v[230:233], v[88:91]
	v_mfma_f32_16x16x32_bf16 v[88:91], v[184:187], v[234:237], v[88:91]
	v_mfma_f32_16x16x32_bf16 v[72:75], v[180:183], v[238:241], v[72:75]
	v_mfma_f32_16x16x32_bf16 v[72:75], v[184:187], v[242:245], v[72:75]
	v_mfma_f32_16x16x32_bf16 v[112:115], v[188:191], v[214:217], v[112:115]
	ds_read_b128 v[214:217], v165 offset:49152
	v_mfma_f32_16x16x32_bf16 v[112:115], v[210:213], v[218:221], v[112:115]
	ds_read_b128 v[218:221], v165 offset:50176
	v_mfma_f32_16x16x32_bf16 v[96:99], v[188:191], v[222:225], v[96:99]
	ds_read_b128 v[222:225], v165 offset:51200
	v_mfma_f32_16x16x32_bf16 v[96:99], v[210:213], v[226:229], v[96:99]
	ds_read_b128 v[226:229], v165 offset:52224
	v_mfma_f32_16x16x32_bf16 v[80:83], v[188:191], v[230:233], v[80:83]
	ds_read_b128 v[230:233], v165 offset:53248
	v_mfma_f32_16x16x32_bf16 v[80:83], v[210:213], v[234:237], v[80:83]
	ds_read_b128 v[234:237], v165 offset:54272
	v_mfma_f32_16x16x32_bf16 v[64:67], v[188:191], v[238:241], v[64:67]
	ds_read_b128 v[238:241], v165 offset:55296
	v_mfma_f32_16x16x32_bf16 v[64:67], v[210:213], v[242:245], v[64:67]
	ds_read_b128 v[242:245], v165 offset:56320
	s_setprio 0
	s_barrier
	s_mov_b32 m0, s37
	s_add_u32 s16, s16, 0x40080
	s_addc_u32 s17, s17, 0
	s_add_u32 s98, s16, 0xfffc0000
	s_addc_u32 s99, s17, -1
	global_load_lds_dwordx4 v132, s[98:99]
	s_mov_b32 m0, s38
	s_nop 0
	global_load_lds_dwordx4 v128, s[98:99]
	s_mov_b32 m0, s41
	s_nop 0
	global_load_lds_dwordx4 v132, s[16:17]
	s_mov_b32 m0, s42
	s_nop 0
	global_load_lds_dwordx4 v128, s[16:17]
	s_mov_b32 m0, s39
	s_nop 0
	s_add_u32 s100, s18, 0xfffc0080
	s_addc_u32 s101, s19, -1
	global_load_lds_dwordx4 v134, s[100:101]
	s_mov_b32 m0, s40
	s_nop 0
	global_load_lds_dwordx4 v130, s[100:101]
	s_waitcnt vmcnt(8)
	s_waitcnt lgkmcnt(0)
	s_barrier
	s_setprio 1
	v_mfma_f32_16x16x32_bf16 v[60:63], v[140:143], v[214:217], v[60:63]
	v_mfma_f32_16x16x32_bf16 v[60:63], v[168:171], v[218:221], v[60:63]
	v_mfma_f32_16x16x32_bf16 v[44:47], v[140:143], v[222:225], v[44:47]
	v_mfma_f32_16x16x32_bf16 v[44:47], v[168:171], v[226:229], v[44:47]
	v_mfma_f32_16x16x32_bf16 v[28:31], v[140:143], v[230:233], v[28:31]
	v_mfma_f32_16x16x32_bf16 v[28:31], v[168:171], v[234:237], v[28:31]
	v_mfma_f32_16x16x32_bf16 v[12:15], v[140:143], v[238:241], v[12:15]
	ds_read_b128 v[140:143], v254
	v_mfma_f32_16x16x32_bf16 v[12:15], v[168:171], v[242:245], v[12:15]
	ds_read_b128 v[168:171], v254 offset:1024
	v_mfma_f32_16x16x32_bf16 v[52:55], v[172:175], v[214:217], v[52:55]
	v_mfma_f32_16x16x32_bf16 v[52:55], v[176:179], v[218:221], v[52:55]
	v_mfma_f32_16x16x32_bf16 v[36:39], v[172:175], v[222:225], v[36:39]
	v_mfma_f32_16x16x32_bf16 v[36:39], v[176:179], v[226:229], v[36:39]
	v_mfma_f32_16x16x32_bf16 v[20:23], v[172:175], v[230:233], v[20:23]
	v_mfma_f32_16x16x32_bf16 v[20:23], v[176:179], v[234:237], v[20:23]
	v_mfma_f32_16x16x32_bf16 v[4:7], v[172:175], v[238:241], v[4:7]
	ds_read_b128 v[172:175], v254 offset:2048
	v_mfma_f32_16x16x32_bf16 v[4:7], v[176:179], v[242:245], v[4:7]
	ds_read_b128 v[176:179], v254 offset:3072
	v_mfma_f32_16x16x32_bf16 v[56:59], v[180:183], v[214:217], v[56:59]
	v_mfma_f32_16x16x32_bf16 v[56:59], v[184:187], v[218:221], v[56:59]
	v_mfma_f32_16x16x32_bf16 v[40:43], v[180:183], v[222:225], v[40:43]
	v_mfma_f32_16x16x32_bf16 v[40:43], v[184:187], v[226:229], v[40:43]
	v_mfma_f32_16x16x32_bf16 v[24:27], v[180:183], v[230:233], v[24:27]
	v_mfma_f32_16x16x32_bf16 v[24:27], v[184:187], v[234:237], v[24:27]
	v_mfma_f32_16x16x32_bf16 v[8:11], v[180:183], v[238:241], v[8:11]
	ds_read_b128 v[180:183], v254 offset:16384
	v_mfma_f32_16x16x32_bf16 v[8:11], v[184:187], v[242:245], v[8:11]
	ds_read_b128 v[184:187], v254 offset:17408
	v_mfma_f32_16x16x32_bf16 v[48:51], v[188:191], v[214:217], v[48:51]
	ds_read_b128 v[214:217], v165
	v_mfma_f32_16x16x32_bf16 v[48:51], v[210:213], v[218:221], v[48:51]
	ds_read_b128 v[218:221], v165 offset:1024
	v_mfma_f32_16x16x32_bf16 v[32:35], v[188:191], v[222:225], v[32:35]
	ds_read_b128 v[222:225], v165 offset:2048
	v_mfma_f32_16x16x32_bf16 v[32:35], v[210:213], v[226:229], v[32:35]
	ds_read_b128 v[226:229], v165 offset:3072
	v_mfma_f32_16x16x32_bf16 v[16:19], v[188:191], v[230:233], v[16:19]
	ds_read_b128 v[230:233], v165 offset:4096
	v_mfma_f32_16x16x32_bf16 v[16:19], v[210:213], v[234:237], v[16:19]
	ds_read_b128 v[234:237], v165 offset:5120
	v_mfma_f32_16x16x32_bf16 v[0:3], v[188:191], v[238:241], v[0:3]
	ds_read_b128 v[188:191], v254 offset:18432
	ds_read_b128 v[238:241], v165 offset:6144
	v_mfma_f32_16x16x32_bf16 v[0:3], v[210:213], v[242:245], v[0:3]
	ds_read_b128 v[210:213], v254 offset:19456
	ds_read_b128 v[242:245], v165 offset:7168
	s_setprio 0
	s_barrier
	s_add_i32 s53, s53, 2
	s_add_u32 s14, s14, 0x100
	s_addc_u32 s15, s15, 0
	s_add_u32 s51, s51, 0x100
	s_addc_u32 s52, s52, 0
	s_cmp_gt_u32 s53, 13
	s_cbranch_scc0 .Lup_loop_w1
	s_waitcnt lgkmcnt(0)
	s_branch .LBB0_449
